# v19: v18 + two-group phase-start offset (odd workgroups of each XCD start the two input-projection GEMM phases ~3us later so epilogue store bursts do not coincide)
# speedup vs baseline: 1.0068x; 1.0026x over previous
.LBB0_147:
	v_readlane_b32 s0, v255, 0
	v_readlane_b32 s4, v255, 9
	v_readlane_b32 s1, v255, 1
	s_mov_b32 s8, s56
	s_mov_b32 s3, s55
	s_waitcnt vmcnt(4)
	v_mov_b32_e32 v18, v254
	v_readlane_b32 s5, v255, 10
	s_andn2_b64 vcc, exec, s[4:5]
	v_readfirstlane_b32 s2, v18
	s_cbranch_vccnz .LBB0_255
	s_bitcmp1_b32 s76, 3
	s_cbranch_scc0 .Lstg_b1
	s_sleep 100
.Lstg_b1:
	v_lshlrev_b32_e32 v1, 4, v18
	v_add_u32_e32 v0, 0x2000, v1
	v_ashrrev_i32_e32 v3, 31, v0
	s_load_dwordx2 s[4:5], s[0:1], 0x60
	v_lshrrev_b32_e32 v3, 22, v3
	v_add_u32_e32 v3, v0, v3
	v_ashrrev_i32_e32 v12, 10, v3
	s_ashr_i32 s9, s8, 31
	v_mul_i32_i24_e32 v3, 0x400, v12
	s_lshl_b64 s[14:15], s[8:9], 24
	s_lshl_b64 s[0:1], s[8:9], 25
	v_sub_u32_e32 v0, v0, v3
	s_waitcnt lgkmcnt(0)
	s_add_u32 s0, s4, s0
	v_lshrrev_b32_e32 v3, 4, v0
	s_addc_u32 s1, s5, s1
	v_bitop3_b32 v0, v3, v0, 32 bitop3:0x6c
	s_add_u32 s30, s0, 0x5000000
	v_ashrrev_i32_e32 v3, 31, v0
	s_addc_u32 s31, s1, 0
	s_ashr_i32 s0, s3, 1
	s_lshl_b32 s3, s3, 24
	v_lshrrev_b32_e32 v3, 26, v3
	s_mul_hi_i32 s1, s0, 0x2600000
	s_mul_i32 s0, s0, 0x2600000
	s_and_b32 s3, s3, 0x1000000
	v_add_u32_e32 v3, v0, v3
	v_lshlrev_b32_e32 v4, 3, v12
	s_add_u32 s0, s4, s0
	v_ashrrev_i32_e32 v13, 6, v3
	v_and_b32_e32 v4, -16, v4
	s_addc_u32 s1, s5, s1
	v_add_u32_e32 v4, v13, v4
	s_add_u32 s34, s0, s3
	v_and_b32_e32 v5, 3, v13
	s_mov_b32 s0, 0x1fffe0
	v_lshrrev_b32_e32 v6, 2, v4
	v_lshlrev_b32_e32 v7, 1, v4
	v_and_b32_e32 v3, 0xc0, v3
	v_and_or_b32 v5, v4, s0, v5
	v_and_b32_e32 v6, 4, v6
	v_and_b32_e32 v7, 24, v7
	v_sub_u32_e32 v0, v0, v3
	v_or3_b32 v5, v5, v6, v7
	v_lshlrev_b32_e32 v6, 5, v12
	v_ashrrev_i16_sdwa v0, v234, sext(v0) dst_sel:DWORD dst_unused:UNUSED_PAD src0_sel:DWORD src1_sel:BYTE_0
	v_and_b32_e32 v6, 32, v6
	v_bfe_i32 v14, v0, 0, 16
	v_add_lshl_u32 v3, v6, v14, 1
	v_lshl_add_u32 v0, v5, 11, v3
	v_lshl_add_u32 v136, v4, 11, v3
	v_bfe_i32 v3, v18, 27, 1
	v_lshrrev_b32_e32 v3, 22, v3
	v_add_u32_e32 v3, v1, v3
	v_and_b32_e32 v3, 0xfffffc00, v3
	v_sub_u32_e32 v1, v1, v3
	v_lshrrev_b32_e32 v3, 4, v1
	v_bitop3_b32 v3, v3, v1, 32 bitop3:0x6c
	v_ashrrev_i32_e32 v1, 31, v1
	v_lshrrev_b32_e32 v1, 26, v1
	v_add_u32_e32 v1, v3, v1
	v_ashrrev_i32_e32 v15, 6, v1
	v_ashrrev_i32_e32 v1, 31, v18
	v_lshrrev_b32_e32 v1, 26, v1
	v_add_u32_e32 v1, v18, v1
	v_ashrrev_i32_e32 v16, 6, v1
	v_lshlrev_b32_e32 v1, 3, v16
	v_and_b32_e32 v1, -16, v1
	v_add_u32_e32 v1, v15, v1
	v_and_b32_e32 v4, 3, v15
	v_lshrrev_b32_e32 v5, 2, v1
	v_lshlrev_b32_e32 v6, 1, v1
	v_and_or_b32 v4, v1, s0, v4
	v_and_b32_e32 v5, 4, v5
	v_and_b32_e32 v6, 24, v6
	v_or3_b32 v4, v4, v5, v6
	v_mul_i32_i24_e32 v6, 64, v15
	s_addc_u32 s35, s1, 0
	s_ashr_i32 s3, s2, 6
	v_sub_u32_e32 v3, v3, v6
	s_ashr_i32 s18, s2, 8
	s_lshl_b32 s36, s3, 10
	v_lshlrev_b32_e32 v5, 5, v16
	v_ashrrev_i16_sdwa v3, v234, sext(v3) dst_sel:DWORD dst_unused:UNUSED_PAD src0_sel:DWORD src1_sel:BYTE_0
	v_readlane_b32 s0, v255, 26
	v_and_b32_e32 v5, 32, v5
	v_bfe_i32 v17, v3, 0, 16
	v_readlane_b32 s1, v255, 27
	s_add_u32 s6, s34, s0
	v_add_lshl_u32 v3, v5, v17, 1
	s_addc_u32 s7, s35, s1
	s_add_i32 s37, s36, 16
	v_lshl_add_u32 v138, v4, 11, v3
	s_add_i32 m0, s37, 0x10000
	v_lshl_add_u32 v140, v1, 11, v3
	global_load_lds_dwordx4 v138, s[6:7]
	s_add_i32 m0, s37, 0x12000
	s_add_u32 s0, s6, 0x40000
	global_load_lds_dwordx4 v0, s[6:7]
	s_addc_u32 s1, s7, 0
	s_add_i32 m0, s37, 0x14000
	v_mov_b32_e32 v139, v2
	global_load_lds_dwordx4 v138, s[0:1]
	s_add_i32 m0, s37, 0x16000
	v_mov_b32_e32 v1, v2
	global_load_lds_dwordx4 v0, s[0:1]
	v_readlane_b32 s0, v255, 24
	v_readlane_b32 s1, v255, 25
	s_add_u32 s0, s30, s0
	s_addc_u32 s1, s31, s1
	s_add_i32 s38, s37, 0x2000
	s_mov_b32 m0, s37
	s_add_u32 s12, s0, 0x40000
	global_load_lds_dwordx4 v140, s[0:1]
	s_mov_b32 m0, s38
	s_addc_u32 s13, s1, 0
	s_add_i32 s39, s37, 0x4000
	global_load_lds_dwordx4 v136, s[0:1]
	s_mov_b32 m0, s39
	s_add_i32 s40, s37, 0x6000
	global_load_lds_dwordx4 v140, s[12:13]
	s_mov_b32 m0, s40
	v_mov_b32_e32 v141, v2
	global_load_lds_dwordx4 v136, s[12:13]
	v_mov_b32_e32 v137, v2
	s_cmp_eq_u32 s18, 1
	v_lshl_add_u64 v[10:11], s[6:7], 0, v[138:139]
	v_lshl_add_u64 v[8:9], s[6:7], 0, v[0:1]
	v_lshl_add_u64 v[4:5], s[0:1], 0, v[140:141]
	s_cselect_b64 s[12:13], -1, 0
	s_cmp_lg_u32 s18, 1
	v_lshl_add_u64 v[6:7], s[0:1], 0, v[136:137]
	s_cbranch_scc1 .LBB0_150
	s_barrier

.LBB0_436:
	s_and_b64 vcc, exec, s[0:1]
	s_cbranch_vccz .LBB0_594
	v_readlane_b32 s0, v255, 0
	v_readlane_b32 s4, v255, 15
	v_readlane_b32 s1, v255, 1
	s_mov_b32 s3, s55
	v_mov_b32_e32 v3, v254
	v_readlane_b32 s5, v255, 16
	s_andn2_b64 vcc, exec, s[4:5]
	v_readfirstlane_b32 s2, v3
	s_cbranch_vccnz .LBB0_473
	s_bitcmp1_b32 s76, 3
	s_cbranch_scc0 .Lstg_a1
	s_sleep 100
.Lstg_a1:
	v_lshlrev_b32_e32 v1, 4, v3
	v_add_u32_e32 v0, 0x2000, v1
	s_waitcnt vmcnt(7) lgkmcnt(0)
	v_ashrrev_i32_e32 v4, 31, v0
	v_lshrrev_b32_e32 v4, 22, v4
	v_add_u32_e32 v4, v0, v4
	s_load_dwordx2 s[4:5], s[0:1], 0x60
	s_waitcnt vmcnt(5)
	v_ashrrev_i32_e32 v12, 10, v4
	v_mul_i32_i24_e32 v4, 0x400, v12
	v_sub_u32_e32 v0, v0, v4
	v_lshrrev_b32_e32 v4, 4, v0
	v_bitop3_b32 v0, v4, v0, 32 bitop3:0x6c
	s_waitcnt lgkmcnt(0)
	s_add_u32 s34, s4, 0x5000000
	v_ashrrev_i32_e32 v4, 31, v0
	s_addc_u32 s35, s5, 0
	s_ashr_i32 s0, s3, 1
	s_lshl_b32 s1, s3, 24
	v_lshrrev_b32_e32 v4, 26, v4
	s_mul_hi_i32 s3, s0, 0x2600000
	s_mul_i32 s0, s0, 0x2600000
	s_and_b32 s1, s1, 0x1000000
	v_add_u32_e32 v4, v0, v4
	v_lshlrev_b32_e32 v5, 3, v12
	s_add_u32 s0, s4, s0
	v_ashrrev_i32_e32 v13, 6, v4
	v_and_b32_e32 v5, -16, v5
	s_addc_u32 s3, s5, s3
	v_add_u32_e32 v5, v13, v5
	s_add_u32 s36, s0, s1
	v_and_b32_e32 v6, 3, v13
	s_mov_b32 s0, 0x1fffe0
	v_lshrrev_b32_e32 v7, 2, v5
	v_lshlrev_b32_e32 v8, 1, v5
	v_and_b32_e32 v4, 0xc0, v4
	v_and_or_b32 v6, v5, s0, v6
	v_and_b32_e32 v7, 4, v7
	v_and_b32_e32 v8, 24, v8
	v_sub_u32_e32 v0, v0, v4
	v_or3_b32 v6, v6, v7, v8
	v_lshlrev_b32_e32 v7, 5, v12
	v_ashrrev_i16_sdwa v0, v234, sext(v0) dst_sel:DWORD dst_unused:UNUSED_PAD src0_sel:DWORD src1_sel:BYTE_0
	v_and_b32_e32 v7, 32, v7
	v_bfe_i32 v14, v0, 0, 16
	v_add_lshl_u32 v4, v7, v14, 1
	v_lshl_add_u32 v0, v6, 11, v4
	v_lshl_add_u32 v132, v5, 11, v4
	v_bfe_i32 v4, v3, 27, 1
	v_lshrrev_b32_e32 v4, 22, v4
	v_add_u32_e32 v4, v1, v4
	v_and_b32_e32 v4, 0xfffffc00, v4
	v_sub_u32_e32 v1, v1, v4
	v_lshrrev_b32_e32 v4, 4, v1
	v_bitop3_b32 v4, v4, v1, 32 bitop3:0x6c
	v_ashrrev_i32_e32 v1, 31, v1
	v_lshrrev_b32_e32 v1, 26, v1
	v_add_u32_e32 v1, v4, v1
	v_ashrrev_i32_e32 v15, 6, v1
	v_ashrrev_i32_e32 v1, 31, v3
	v_lshrrev_b32_e32 v1, 26, v1
	v_add_u32_e32 v1, v3, v1
	s_waitcnt vmcnt(4)
	v_ashrrev_i32_e32 v16, 6, v1
	v_lshlrev_b32_e32 v1, 3, v16
	v_and_b32_e32 v1, -16, v1
	v_add_u32_e32 v1, v15, v1
	v_and_b32_e32 v5, 3, v15
	v_lshrrev_b32_e32 v6, 2, v1
	v_lshlrev_b32_e32 v7, 1, v1
	v_and_or_b32 v5, v1, s0, v5
	v_and_b32_e32 v6, 4, v6
	v_and_b32_e32 v7, 24, v7
	v_or3_b32 v5, v5, v6, v7
	v_mul_i32_i24_e32 v7, 64, v15
	s_addc_u32 s37, s3, 0
	s_ashr_i32 s6, s2, 6
	v_sub_u32_e32 v4, v4, v7
	s_ashr_i32 s3, s2, 8
	s_lshl_b32 s38, s6, 10
	v_lshlrev_b32_e32 v6, 5, v16
	v_ashrrev_i16_sdwa v4, v234, sext(v4) dst_sel:DWORD dst_unused:UNUSED_PAD src0_sel:DWORD src1_sel:BYTE_0
	v_readlane_b32 s0, v255, 32
	v_and_b32_e32 v6, 32, v6
	v_bfe_i32 v17, v4, 0, 16
	v_readlane_b32 s1, v255, 33
	s_add_u32 s28, s36, s0
	v_add_lshl_u32 v4, v6, v17, 1
	s_addc_u32 s29, s37, s1
	s_add_i32 s39, s38, 16
	v_lshl_add_u32 v134, v5, 11, v4
	s_add_i32 m0, s39, 0x10000
	v_lshl_add_u32 v136, v1, 11, v4
	global_load_lds_dwordx4 v134, s[28:29]
	s_add_i32 m0, s39, 0x12000
	s_add_u32 s0, s28, 0x40000
	global_load_lds_dwordx4 v0, s[28:29]
	s_addc_u32 s1, s29, 0
	s_add_i32 m0, s39, 0x14000
	v_mov_b32_e32 v135, v2
	global_load_lds_dwordx4 v134, s[0:1]
	s_add_i32 m0, s39, 0x16000
	v_mov_b32_e32 v1, v2
	global_load_lds_dwordx4 v0, s[0:1]
	v_readlane_b32 s0, v255, 30
	v_readlane_b32 s1, v255, 31
	s_add_u32 s0, s34, s0
	s_addc_u32 s1, s35, s1
	s_add_i32 s40, s39, 0x2000
	s_mov_b32 m0, s39
	s_add_u32 s8, s0, 0x40000
	global_load_lds_dwordx4 v136, s[0:1]
	s_mov_b32 m0, s40
	s_addc_u32 s9, s1, 0
	s_add_i32 s41, s39, 0x4000
	global_load_lds_dwordx4 v132, s[0:1]
	s_mov_b32 m0, s41
	s_add_i32 s42, s39, 0x6000
	global_load_lds_dwordx4 v136, s[8:9]
	s_mov_b32 m0, s42
	v_mov_b32_e32 v137, v2
	global_load_lds_dwordx4 v132, s[8:9]
	v_mov_b32_e32 v133, v2
	s_cmp_eq_u32 s3, 1
	v_lshl_add_u64 v[10:11], s[28:29], 0, v[134:135]
	v_lshl_add_u64 v[8:9], s[28:29], 0, v[0:1]
	v_lshl_add_u64 v[4:5], s[0:1], 0, v[136:137]
	s_cselect_b64 s[8:9], -1, 0
	s_cmp_lg_u32 s3, 1
	v_lshl_add_u64 v[6:7], s[0:1], 0, v[132:133]
	s_cbranch_scc1 .LBB0_440
	s_barrier
